# stagger up-GEMM start: WGs with (bid>>3)&1 delayed by 2x s_sleep 127
# speedup vs baseline: 1.0212x; 1.0070x over previous
; __global__ void __launch_bounds__(512, 2) mega_fwd(Args args) {
;     ...
;     for (int ph = args.ph_lo; ph < args.ph_hi; ++ph) {
;         const int l = ph / PH_PER_LAYER, k = ph % PH_PER_LAYER;
;         { int t_ = threadIdx.x; asm volatile("" : "+v"(t_)); c.tid = t_; c.lane = t_ & 63; c.wave = __builtin_amdgcn_readfirstlane(t_ >> 6);
;           int z_ = 0; asm volatile("" : "+s"(z_)); c.zero = z_;
;           int bx = blockIdx.x; asm volatile("" : "+s"(bx)); c.vcu = (c.G % 8 == 0) ? (bx % 8) * (c.G / 8) + bx / 8 : bx; }
;     ...
;         if (k == 0) {
;     ...
;         } else if (k == 5) {
;             pg8::Gemm g{XB, (const bf16_t*)(c.ws + WS_WUP), MTOK, 1024, 1024}; pg8::StaticOrder S; S.init(MTOK, 1024, c.G, (int)blockIdx.x);
;             pg8::EpiUp E{(const bf16_t*)(c.ws + WS_Z + 6 * ZARR), (bf16_t*)(c.ws + WS_Z + 1 * ZARR)};
;             int nrep_ = (REPMASK & 32) ? 2 : 1; asm volatile("" : "+s"(nrep_));
;             for (int r_ = 0; r_ < nrep_; ++r_) { if (PHMASK & 32) pg8::gemm_phase<pg8::EpiUp, pg8::StaticOrder, true, true>(lds3, g, S, E); __syncthreads(); }
.LBB0_22:
	v_readlane_b32 s12, v253, 4
	s_mul_hi_i32 s0, s12, 0x92492493
	s_add_i32 s0, s0, s12
	s_lshr_b32 s6, s0, 31
	s_ashr_i32 s0, s0, 2
	s_add_i32 s80, s0, s6
	s_mul_i32 s0, s80, 7
	v_readlane_b32 s13, v253, 5
	s_sub_i32 s92, s12, s0
	v_writelane_b32 v252, s16, 46
	s_ashr_i32 s0, s16, 6
	v_and_b32_e32 v200, 63, v201
	v_writelane_b32 v252, s0, 47
	s_mov_b64 s[38:39], -1
	s_mov_b64 s[12:13], 0
	s_cmp_lt_i32 s92, 3
	s_mov_b64 s[76:77], 0
	v_writelane_b32 v252, s24, 48
	s_cbranch_scc1 .LBB0_308
	s_cmp_gt_i32 s92, 3
	v_writelane_b32 v252, s92, 49
	s_cbranch_scc0 .LBB0_90
	s_cmp_gt_i32 s92, 4
	s_cbranch_scc0 .LBB0_62
	s_cmp_eq_u32 s92, 5
	s_mov_b64 s[76:77], -1
	s_cbranch_scc0 .LBB0_61
	s_lshr_b32 s98, s2, 3
	s_and_b32 s98, s98, 1
	s_mul_i32 s98, s98, 2
	s_cmp_eq_u32 s98, 0
	s_cbranch_scc1 .Lstag5_done

; __global__ void __launch_bounds__(512, 2) mega_fwd(Args args) {
;     ...
;         } else if (k == 5) {
;             pg8::Gemm g{XB, (const bf16_t*)(c.ws + WS_WUP), MTOK, 1024, 1024}; pg8::StaticOrder S; S.init(MTOK, 1024, c.G, (int)blockIdx.x);
;             pg8::EpiUp E{(const bf16_t*)(c.ws + WS_Z + 6 * ZARR), (bf16_t*)(c.ws + WS_Z + 1 * ZARR)};
;             int nrep_ = (REPMASK & 32) ? 2 : 1; asm volatile("" : "+s"(nrep_));
;             for (int r_ = 0; r_ < nrep_; ++r_) { if (PHMASK & 32) pg8::gemm_phase<pg8::EpiUp, pg8::StaticOrder, true, true>(lds3, g, S, E); __syncthreads(); }
.Lstag5_done:
	s_mov_b32 s6, 1
	s_cmp_lt_i32 s6, 1
	s_cbranch_scc1 .LBB0_60
	v_writelane_b32 v252, s80, 54
	s_mov_b32 s22, 0
	s_nop 0
	v_writelane_b32 v252, s81, 55
	v_writelane_b32 v252, s72, 52
	s_nop 1
	v_writelane_b32 v252, s73, 53
	v_writelane_b32 v252, s6, 50
	s_branch .LBB0_30
